# w_in: workgroups of XCDs 4-7 run the narrow strip pass before their seven rounds, XCDs 0-3 after (the two halves' epilogue store bursts no longer coincide)
# speedup vs baseline: 1.0026x; 1.0026x over previous
.Lg2_win_entry:
	s_waitcnt vmcnt(0) lgkmcnt(0)
	s_barrier
	v_mov_b32_e32 v2, 0x10200
	ds_read_b64 v[2:3], v2
	v_readlane_b32 s0, v246, 0
	v_lshrrev_b32_e32 v4, 6, v163
	v_and_b32_e32 v5, 63, v163
	s_and_b32 s1, s0, 7
	s_lshr_b32 s0, s0, 3
	s_lshr_b32 s68, s0, 3
	s_and_b32 s0, s0, 7
	s_lshl_b32 s0, s0, 3
	s_add_i32 s0, s0, s1
	s_cmp_lt_u32 s0, 32
	s_cselect_b32 s43, 1, 0
	s_min_u32 s1, s0, 32
	s_lshl_b32 s0, s0, 4
	s_add_i32 s0, s0, s1
	s_lshl_b32 s42, s0, 4
	v_readfirstlane_b32 s70, v4
	v_and_b32_e32 v6, 15, v5
	v_lshrrev_b32_e32 v7, 4, v5
	s_waitcnt lgkmcnt(0)
	v_readfirstlane_b32 s66, v2
	v_readfirstlane_b32 s67, v3
	s_lshl_b32 s62, s70, 10
	v_and_b32_e32 v8, 7, v6
	v_xor_b32_e32 v9, v7, v8
	v_lshlrev_b32_e32 v9, 4, v9
	v_lshl_add_u32 v156, v6, 7, v9
	v_add_u32_e32 v10, 4, v7
	v_xor_b32_e32 v10, v10, v8
	v_lshlrev_b32_e32 v10, 4, v10
	v_lshl_add_u32 v157, v6, 7, v10
	v_add_u32_e32 v158, 0x8800, v156
	v_add_u32_e32 v159, 0x8800, v157
	v_lshrrev_b32_e32 v11, 3, v163
	v_and_b32_e32 v12, 7, v163
	v_and_b32_e32 v13, 7, v11
	v_xor_b32_e32 v12, v12, v13
	v_lshlrev_b32_e32 v12, 4, v12
	s_mov_b32 s2, 0x800
	v_mul_lo_u32 v11, v11, s2
	v_add_u32_e32 v162, v11, v12
	v_lshrrev_b32_e32 v11, 4, v163
	v_and_b32_e32 v12, 15, v163
	v_xor_b32_e32 v13, v12, v11
	v_lshlrev_b32_e32 v13, 4, v13
	v_lshl_add_u32 v247, v11, 8, v13
	s_mov_b32 s2, 0x3900
	v_mul_lo_u32 v11, v11, s2
	v_lshl_add_u32 v252, v12, 4, v11
	v_add_u32_e32 v255, 0x8000, v247
	v_readlane_b32 s0, v246, 0
	s_bfe_u32 s71, s0, 0x10002
	s_cmp_lg_u32 s71, 0
	s_cbranch_scc1 .Lg2_win_strip
.Lg2_win_main:
	v_lshrrev_b32_e32 v4, 6, v163
	v_and_b32_e32 v5, 63, v163
	v_and_b32_e32 v6, 15, v5
	v_lshrrev_b32_e32 v7, 4, v5
	v_lshrrev_b32_e32 v11, 1, v4
	v_and_b32_e32 v12, 1, v4
	v_lshl_add_u32 v11, v11, 2, v12
	s_mov_b32 s2, 0x8000
	v_mul_lo_u32 v12, v11, s2
	v_lshl_add_u32 v160, v5, 4, v12
	v_add_u32_e32 v161, 0x10000, v160
	v_lshrrev_b32_e32 v12, 1, v7
	v_lshl_add_u32 v12, v11, 1, v12
	v_and_b32_e32 v13, 1, v7
	v_lshlrev_b32_e32 v13, 3, v13
	v_lshl_add_u32 v14, v6, 8, v13
	v_xor_b32_e32 v15, v12, v6
	v_lshlrev_b32_e32 v15, 4, v15
	v_add_u32_e32 v212, v14, v15
	v_add_u32_e32 v12, 4, v12
	v_xor_b32_e32 v15, v12, v6
	v_lshlrev_b32_e32 v15, 4, v15
	v_add_u32_e32 v213, v14, v15
	v_add_u32_e32 v253, 0x8000, v212
	v_add_u32_e32 v254, 0x8000, v213
	s_mov_b32 s64, 0

.Lg2_win_next:
	s_add_i32 s64, s64, 1
	s_cmp_lt_u32 s64, 7
	s_cbranch_scc1 .Lg2_win_tile
	s_cmp_lg_u32 s71, 0
	s_cbranch_scc1 .Lg2_win_exit
.Lg2_win_strip:
	v_lshrrev_b32_e32 v4, 6, v163
	v_and_b32_e32 v5, 63, v163
	v_and_b32_e32 v6, 15, v5
	v_lshrrev_b32_e32 v7, 4, v5
	v_lshlrev_b32_e32 v11, 1, v4
	s_mov_b32 s2, 0x8000
	v_mul_lo_u32 v12, v11, s2
	v_lshl_add_u32 v160, v5, 4, v12
	v_add_u32_e32 v161, 0x8000, v160
	v_lshrrev_b32_e32 v12, 1, v7
	v_lshl_add_u32 v12, v11, 1, v12
	v_and_b32_e32 v13, 1, v7
	v_lshlrev_b32_e32 v13, 3, v13
	v_lshl_add_u32 v14, v6, 8, v13
	v_xor_b32_e32 v15, v12, v6
	v_lshlrev_b32_e32 v15, 4, v15
	v_add_u32_e32 v212, v14, v15
	v_add_u32_e32 v12, 2, v12
	v_xor_b32_e32 v15, v12, v6
	v_lshlrev_b32_e32 v15, 4, v15
	v_add_u32_e32 v213, v14, v15
	v_add_u32_e32 v253, 0x8000, v212
	v_add_u32_e32 v254, 0x8000, v213
	s_mov_b32 s38, 56
	s_lshl_b32 s0, s68, 5
	s_add_i32 s69, s42, s0
	s_cmp_eq_u32 s68, 7
	s_cselect_b32 s0, 1, 0
	s_and_b32 s65, s0, s43
	s_lshl_b32 s0, s38, 7
	s_mul_i32 s2, s69, 0x800
	s_mul_hi_u32 s3, s69, 0x800
	s_add_u32 s56, s26, s2
	s_addc_u32 s57, s27, s3
	s_add_u32 s56, s56, 0x11140000
	s_addc_u32 s57, s57, 0
	s_mul_i32 s2, s0, 0x800
	s_mul_hi_u32 s3, s0, 0x800
	s_add_u32 s58, s26, s2
	s_addc_u32 s59, s27, s3
	s_add_u32 s58, s58, 0xeb20000
	s_addc_u32 s59, s59, 0
	s_mul_i32 s2, s69, 0x3900
	s_mul_hi_u32 s3, s69, 0x3900
	s_lshl_b32 s0, s0, 1
	s_add_u32 s2, s2, s0
	s_addc_u32 s3, s3, 0
	s_add_u32 s60, s26, s2
	s_addc_u32 s61, s27, s3
	s_add_u32 s60, s60, 0x0
	s_addc_u32 s61, s61, 0
	s_cmp_eq_u32 s65, 0
	s_cbranch_scc1 .Lg2_win_k2
	s_add_u32 m0, s62, 0x0
	s_add_u32 s4, s56, 0x0
	s_addc_u32 s5, s57, 0
	global_load_lds_dwordx4 v162, s[4:5]
	s_cmp_gt_u32 s70, 1
	s_cbranch_scc1 .Lg2_win_nodma_4
	s_add_u32 m0, s62, 0x1000
	s_add_u32 s4, s56, 0x10000
	s_addc_u32 s5, s57, 0
	global_load_lds_dwordx4 v162, s[4:5]

.Lg2_win_stripdone:
	s_cmp_lg_u32 s71, 0
	s_cbranch_scc1 .Lg2_win_main
